# P1: workgroups 128..255 (19 tiles) start half a tile late so the two chip halves do not store their epilogues at the same time
# speedup vs baseline: 1.0037x; 1.0037x over previous
; #define PG8_STAGE(bufoff, gbase, voff) do { _Pragma("unroll") for (int _i = 0; _i < 2; ++_i) \
;         __builtin_amdgcn_global_load_lds((const unsigned*)((const char*)(gbase) + (voff)[_i]), (LAS unsigned*)(lds + (bufoff) + ldsw + _i * 8192), 16, 0, 0); } while (0)
; #define PG8_BAR __builtin_amdgcn_s_barrier()
; template <class Epi>
; __device__ __forceinline__ void gemm_phase(LAS unsigned char* lds, const Gemm g, const StaticOrder& S, const Epi& E, const int wid) {
;     const int lane = lane_id(), tid = wid * 64 + lane, wr = wid >> 2, wc = wid & 3, fr = lane & 15, fq = lane >> 4;
;     const int K = g.K, nt = K / BK, lda = g.lda;
;     unsigned voffA[2], voffB[2];
; #pragma unroll
;     for (int i = 0; i < 2; ++i) { int R, C; stage_rc(tid * 16 + i * 8192, R, C); const int Rb = (R & ~31) + perm32(R & 31);
;         voffA[i] = (unsigned)(R * lda + C) * 2u; voffB[i] = (unsigned)(Rb * K + C) * 2u; }
;     const size_t kstep = (size_t)(BK * 2);
;     const size_t hstepA = (size_t)HALF * lda * 2, hstepB = (size_t)HALF * K * 2;
;     const unsigned ldsw = (unsigned)wid * 1024u;
;     const int aoff = lds_byte(wr * 64 + fr, fq * 8), boff = lds_byte(wc * 32 + fr, fq * 8);
;     ...
;     Unit cur, nxt; int ui = 0;
;     if (!S.next(0, cur)) return;
;     f32x4 acc[2][2][4][2];
; #pragma unroll
;     for (int a = 0; a < 2; ++a)
; #pragma unroll
;         for (int b = 0; b < 2; ++b)
; #pragma unroll
;             for (int m = 0; m < 4; ++m)
; #pragma unroll
;                 for (int n = 0; n < 2; ++n) acc[a][b][m][n] = (f32x4){0.f, 0.f, 0.f, 0.f};
;     bf16x8 At[4][2], B0[2][2], B1[2][2];
;     const char* cA = PG8_TILEA(cur.pm); const char* cB = PG8_TILEB(cur.pn);
;     PG8_STAGE(PG8_SB(0, 0), cB, voffB); PG8_STAGE(PG8_SB(0, 1), cB + hstepB, voffB); PG8_STAGE(PG8_SA(0, 0), cA, voffA); PG8_STAGE(PG8_SA(0, 1), cA + hstepA, voffA);
;     if (wr == 1) PG8_BAR;
;     PG8_WAIT_V(2); PG8_BAR;
;     PG8_STAGE(PG8_SB(1, 0), cB + kstep, voffB); PG8_STAGE(PG8_SA(1, 0), cA + kstep, voffA); PG8_STAGE(PG8_SB(1, 1), cB + hstepB + kstep, voffB);
;     PG8_WAIT_V(6); PG8_BAR;
; __global__ void __launch_bounds__(512, 2) mega_fwd(Args args) {
;     ...
;         pg8::Gemm g{XN, (const bf16_t*)(ws + WS_WIN), TOK, NPROJ, DM, DM, TOK / 256, 0};
;         pg8::StaticOrder S; S.init(TOK, NPROJ, G, bx);
;         pg8::EpiProj E{ws};
;         pg8::gemm_phase(ldsl, g, S, E, wave);
.LBB0_146:
	s_andn2_b64 vcc, exec, s[2:3]
	s_cbranch_vccnz .LBB0_404
	s_cmp_lt_u32 s89, 128
	s_cbranch_scc1 .Lp1s_nodelay
	s_mov_b32 s98, 2900
	s_memrealtime s[100:101]
	s_waitcnt lgkmcnt(0)
	s_mov_b32 s99, s100
.Lp1s_spin:
	s_sleep 20
	s_memrealtime s[100:101]
	s_waitcnt lgkmcnt(0)
	s_sub_u32 s100, s100, s99
	s_cmp_lt_u32 s100, s98
	s_cbranch_scc1 .Lp1s_spin
.Lp1s_nodelay:
	s_lshl_b32 s4, s12, 1
	v_lshlrev_b32_e32 v0, 4, v8
	v_and_b32_e32 v1, 32, v8
	v_lshrrev_b32_e32 v2, 1, v8
	s_and_b32 s4, s4, 4
	v_bfe_u32 v9, v0, 6, 4
	v_bitop3_b32 v10, v0, v1, 48 bitop3:0x6c
	v_and_b32_e32 v11, 24, v2
	v_bfe_u32 v0, v0, 6, 2
	s_lshl_b32 s0, s33, 3
	v_or3_b32 v0, v0, s4, v11
	s_and_b32 s1, s0, 48
	v_and_or_b32 v3, s0, 32, v0
	s_ashr_i32 s0, s44, 31
	s_lshr_b32 s0, s0, 25
	s_add_i32 s0, s44, s0
	s_and_b32 s0, s0, 0xffffff80
	s_or_b32 s2, s1, 64
	s_and_b32 s6, s92, 64
	s_sub_i32 s0, s44, s0
	s_and_b32 s3, s2, 0x60
	v_or_b32_e32 v1, s6, v10
	v_or_b32_e32 v2, s1, v9
	s_ashr_i32 s1, s0, 31
	s_ashr_i32 s55, s54, 31
	v_lshl_or_b32 v128, v2, 12, v1
	v_or_b32_e32 v2, s2, v9
	v_or_b32_e32 v0, s3, v0
	s_lshl_b64 s[2:3], s[0:1], 20
	s_lshl_b64 s[0:1], s[54:55], 20
	s_add_u32 s56, s36, s0
	s_addc_u32 s57, s37, s1
	s_add_i32 s0, s94, 0
	v_lshl_or_b32 v130, v3, 12, v1
	s_add_i32 m0, s0, 0x10000
	v_lshl_or_b32 v134, v0, 12, v1
	global_load_lds_dwordx4 v130, s[56:57]
	s_add_i32 m0, s0, 0x12000
	s_add_u32 s4, s56, 0x80000
	global_load_lds_dwordx4 v134, s[56:57]
	s_addc_u32 s5, s57, 0
	s_add_i32 m0, s0, 0x14000
	v_lshl_or_b32 v132, v2, 12, v1
	global_load_lds_dwordx4 v130, s[4:5]
	s_add_i32 m0, s0, 0x16000
	s_add_u32 s10, s30, s2
	s_addc_u32 s11, s31, s3
	s_add_i32 s1, s0, 0x2000
	global_load_lds_dwordx4 v134, s[4:5]
	s_mov_b32 m0, s0
	s_add_u32 s2, s10, 0x80000
	global_load_lds_dwordx4 v128, s[10:11]
	s_mov_b32 m0, s1
	s_addc_u32 s3, s11, 0
	s_add_i32 s15, s0, 0x4000
	global_load_lds_dwordx4 v132, s[10:11]
	s_mov_b32 m0, s15
	s_add_i32 s26, s0, 0x6000
	global_load_lds_dwordx4 v128, s[2:3]
	s_mov_b32 m0, s26
	v_readlane_b32 s4, v251, 30
	global_load_lds_dwordx4 v132, s[2:3]
	v_mov_b32_e32 v137, 0
	v_readlane_b32 s5, v251, 31
	v_mov_b32_e32 v131, v137
	v_mov_b32_e32 v135, v137
	v_mov_b32_e32 v129, v137
	v_mov_b32_e32 v133, v137
	v_cndmask_b32_e64 v6, 0, 1, s[4:5]
	s_mov_b32 s73, s45
	s_movk_i32 s27, 0x60
	v_lshl_add_u64 v[4:5], s[56:57], 0, v[130:131]
	s_mov_b32 s45, 0
	v_lshl_add_u64 v[2:3], s[56:57], 0, v[134:135]
	v_lshl_add_u64 v[0:1], s[10:11], 0, v[128:129]
	v_cmp_ne_u32_e64 s[2:3], 1, v6
	s_andn2_b64 vcc, exec, s[4:5]
	v_lshl_add_u64 v[6:7], s[10:11], 0, v[132:133]
	s_cbranch_vccnz .LBB0_149
	s_barrier
